# EpiResid: 32 ds_bpermute cross-lane reductions per tile replaced by v_permlane16/32_swap (no LDS round trips)
# speedup vs baseline: 1.0079x; 1.0079x over previous
.LBB0_1071:
	v_and_b32_e32 v95, 64, v242
	v_xor_b32_e32 v94, 16, v242
	v_add_u32_e32 v95, 64, v95
	v_cmp_lt_i32_e32 vcc, v94, v95
	v_mul_f32_e32 v96, v149, v149
	v_fmac_f32_e32 v96, v148, v148
	v_cndmask_b32_e32 v94, v242, v94, vcc
	v_lshlrev_b32_e32 v245, 2, v94
	v_mul_f32_e32 v94, v147, v147
	v_fmac_f32_e32 v94, v146, v146
	v_add_f32_e32 v94, v94, v96
	v_mul_f32_e32 v96, v143, v143
	v_mul_f32_e32 v97, v145, v145
	v_fmac_f32_e32 v96, v142, v142
	v_fmac_f32_e32 v97, v144, v144
	v_add_f32_e32 v96, v96, v97
	v_add_f32_e32 v94, v96, v94
	v_mul_f32_e32 v96, v139, v139
	v_mul_f32_e32 v97, v141, v141
	v_fmac_f32_e32 v96, v138, v138
	v_fmac_f32_e32 v97, v140, v140
	v_add_f32_e32 v96, v96, v97
	v_add_f32_e32 v94, v96, v94
	v_mul_f32_e32 v96, v135, v135
	v_mul_f32_e32 v97, v137, v137
	v_fmac_f32_e32 v96, v134, v134
	v_fmac_f32_e32 v97, v136, v136
	v_add_f32_e32 v96, v96, v97
	v_add_f32_e32 v94, v96, v94
	v_mov_b32_e32 v96, v94
	s_nop 1
	v_permlane16_swap_b32_e32 v94, v96
	v_xor_b32_e32 v97, 32, v242
	v_cmp_lt_i32_e32 vcc, v97, v95
	s_waitcnt lgkmcnt(0)
	v_add_f32_e32 v94, v94, v96
	v_cndmask_b32_e32 v95, v242, v97, vcc
	v_lshlrev_b32_e32 v246, 2, v95
	v_mov_b32_e32 v95, v94
	s_nop 1
	v_permlane32_swap_b32_e32 v94, v95
	s_and_saveexec_b64 s[30:31], s[4:5]
	s_cbranch_execz .LBB0_1073
	s_waitcnt lgkmcnt(0)
	v_add_f32_e32 v94, v94, v95
	ds_write_b32 v228, v94
.LBB0_1073:
	s_or_b64 exec, exec, s[30:31]
	v_mul_f32_e32 v94, v131, v131
	s_waitcnt lgkmcnt(0)
	v_mul_f32_e32 v95, v133, v133
	v_fmac_f32_e32 v94, v130, v130
	v_fmac_f32_e32 v95, v132, v132
	v_add_f32_e32 v94, v94, v95
	v_mul_f32_e32 v95, v127, v127
	v_mul_f32_e32 v96, v129, v129
	v_fmac_f32_e32 v95, v126, v126
	v_fmac_f32_e32 v96, v128, v128
	v_add_f32_e32 v95, v95, v96
	v_add_f32_e32 v94, v95, v94
	v_mul_f32_e32 v95, v123, v123
	v_mul_f32_e32 v96, v125, v125
	v_fmac_f32_e32 v95, v122, v122
	v_fmac_f32_e32 v96, v124, v124
	v_add_f32_e32 v95, v95, v96
	v_add_f32_e32 v94, v95, v94
	v_mul_f32_e32 v95, v119, v119
	v_mul_f32_e32 v96, v121, v121
	v_fmac_f32_e32 v95, v118, v118
	v_fmac_f32_e32 v96, v120, v120
	v_add_f32_e32 v95, v95, v96
	v_add_f32_e32 v94, v95, v94
	v_mov_b32_e32 v95, v94
	s_nop 1
	v_permlane16_swap_b32_e32 v94, v95
	s_waitcnt lgkmcnt(0)
	v_add_f32_e32 v94, v94, v95
	v_mov_b32_e32 v95, v94
	s_nop 1
	v_permlane32_swap_b32_e32 v94, v95
	s_and_saveexec_b64 s[30:31], s[4:5]
	s_cbranch_execz .LBB0_1075
	s_waitcnt lgkmcnt(0)
	v_add_f32_e32 v94, v94, v95
	ds_write_b32 v228, v94 offset:256
.LBB0_1075:
	s_or_b64 exec, exec, s[30:31]
	v_mul_f32_e32 v94, v107, v107
	s_waitcnt lgkmcnt(0)
	v_mul_f32_e32 v95, v109, v109
	v_fmac_f32_e32 v94, v106, v106
	v_fmac_f32_e32 v95, v108, v108
	v_add_f32_e32 v94, v94, v95
	v_mul_f32_e32 v95, v99, v99
	v_mul_f32_e32 v96, v101, v101
	v_fmac_f32_e32 v95, v98, v98
	v_fmac_f32_e32 v96, v100, v100
	v_add_f32_e32 v95, v95, v96
	v_add_f32_e32 v94, v95, v94
	v_mul_f32_e32 v95, v91, v91
	v_mul_f32_e32 v96, v93, v93
	v_fmac_f32_e32 v95, v90, v90
	v_fmac_f32_e32 v96, v92, v92
	v_add_f32_e32 v95, v95, v96
	v_add_f32_e32 v94, v95, v94
	v_mul_f32_e32 v95, v87, v87
	v_mul_f32_e32 v96, v89, v89
	v_fmac_f32_e32 v95, v86, v86
	v_fmac_f32_e32 v96, v88, v88
	v_add_f32_e32 v95, v95, v96
	v_add_f32_e32 v94, v95, v94
	v_mov_b32_e32 v95, v94
	s_nop 1
	v_permlane16_swap_b32_e32 v94, v95
	s_waitcnt lgkmcnt(0)
	v_add_f32_e32 v94, v94, v95
	v_mov_b32_e32 v95, v94
	s_nop 1
	v_permlane32_swap_b32_e32 v94, v95
	s_and_saveexec_b64 s[30:31], s[4:5]
	s_cbranch_execz .LBB0_1077
	s_waitcnt lgkmcnt(0)
	v_add_f32_e32 v94, v94, v95
	ds_write_b32 v228, v94 offset:512
.LBB0_1077:
	s_or_b64 exec, exec, s[30:31]
	v_mul_f32_e32 v94, v83, v83
	s_waitcnt lgkmcnt(0)
	v_mul_f32_e32 v95, v85, v85
	v_fmac_f32_e32 v94, v82, v82
	v_fmac_f32_e32 v95, v84, v84
	v_add_f32_e32 v94, v94, v95
	v_mul_f32_e32 v95, v79, v79
	v_mul_f32_e32 v96, v81, v81
	v_fmac_f32_e32 v95, v78, v78
	v_fmac_f32_e32 v96, v80, v80
	v_add_f32_e32 v95, v95, v96
	v_add_f32_e32 v94, v95, v94
	v_mul_f32_e32 v95, v75, v75
	v_mul_f32_e32 v96, v77, v77
	v_fmac_f32_e32 v95, v74, v74
	v_fmac_f32_e32 v96, v76, v76
	v_add_f32_e32 v95, v95, v96
	v_add_f32_e32 v94, v95, v94
	v_mul_f32_e32 v95, v71, v71
	v_mul_f32_e32 v96, v73, v73
	v_fmac_f32_e32 v95, v70, v70
	v_fmac_f32_e32 v96, v72, v72
	v_add_f32_e32 v95, v95, v96
	v_add_f32_e32 v94, v95, v94
	v_mov_b32_e32 v95, v94
	s_nop 1
	v_permlane16_swap_b32_e32 v94, v95
	s_waitcnt lgkmcnt(0)
	v_add_f32_e32 v94, v94, v95
	v_mov_b32_e32 v95, v94
	s_nop 1
	v_permlane32_swap_b32_e32 v94, v95
	s_and_saveexec_b64 s[30:31], s[4:5]
	s_cbranch_execz .LBB0_1079
	s_waitcnt lgkmcnt(0)
	v_add_f32_e32 v94, v94, v95
	ds_write_b32 v228, v94 offset:768
.LBB0_1079:
	s_or_b64 exec, exec, s[30:31]
	v_mul_f32_e32 v94, v67, v67
	s_waitcnt lgkmcnt(0)
	v_mul_f32_e32 v95, v69, v69
	v_fmac_f32_e32 v94, v66, v66
	v_fmac_f32_e32 v95, v68, v68
	v_add_f32_e32 v94, v94, v95
	v_mul_f32_e32 v95, v63, v63
	v_mul_f32_e32 v96, v65, v65
	v_fmac_f32_e32 v95, v62, v62
	v_fmac_f32_e32 v96, v64, v64
	v_add_f32_e32 v95, v95, v96
	v_add_f32_e32 v94, v95, v94
	v_mul_f32_e32 v95, v59, v59
	v_mul_f32_e32 v96, v61, v61
	v_fmac_f32_e32 v95, v58, v58
	v_fmac_f32_e32 v96, v60, v60
	v_add_f32_e32 v95, v95, v96
	v_add_f32_e32 v94, v95, v94
	v_mul_f32_e32 v95, v55, v55
	v_mul_f32_e32 v96, v57, v57
	v_fmac_f32_e32 v95, v54, v54
	v_fmac_f32_e32 v96, v56, v56
	v_add_f32_e32 v95, v95, v96
	v_add_f32_e32 v94, v95, v94
	v_mov_b32_e32 v95, v94
	s_nop 1
	v_permlane16_swap_b32_e32 v94, v95
	s_waitcnt lgkmcnt(0)
	v_add_f32_e32 v94, v94, v95
	v_mov_b32_e32 v95, v94
	s_nop 1
	v_permlane32_swap_b32_e32 v94, v95
	s_and_saveexec_b64 s[30:31], s[4:5]
	s_cbranch_execz .LBB0_1081
	s_waitcnt lgkmcnt(0)
	v_add_f32_e32 v94, v94, v95
	ds_write_b32 v228, v94 offset:2048
.LBB0_1081:
	s_or_b64 exec, exec, s[30:31]
	v_mul_f32_e32 v94, v51, v51
	s_waitcnt lgkmcnt(0)
	v_mul_f32_e32 v95, v53, v53
	v_fmac_f32_e32 v94, v50, v50
	v_fmac_f32_e32 v95, v52, v52
	v_add_f32_e32 v94, v94, v95
	v_mul_f32_e32 v95, v47, v47
	v_mul_f32_e32 v96, v49, v49
	v_fmac_f32_e32 v95, v46, v46
	v_fmac_f32_e32 v96, v48, v48
	v_add_f32_e32 v95, v95, v96
	v_add_f32_e32 v94, v95, v94
	v_mul_f32_e32 v95, v43, v43
	v_mul_f32_e32 v96, v45, v45
	v_fmac_f32_e32 v95, v42, v42
	v_fmac_f32_e32 v96, v44, v44
	v_add_f32_e32 v95, v95, v96
	v_add_f32_e32 v94, v95, v94
	v_mul_f32_e32 v95, v39, v39
	v_mul_f32_e32 v96, v41, v41
	v_fmac_f32_e32 v95, v38, v38
	v_fmac_f32_e32 v96, v40, v40
	v_add_f32_e32 v95, v95, v96
	v_add_f32_e32 v94, v95, v94
	v_mov_b32_e32 v95, v94
	s_nop 1
	v_permlane16_swap_b32_e32 v94, v95
	s_waitcnt lgkmcnt(0)
	v_add_f32_e32 v94, v94, v95
	v_mov_b32_e32 v95, v94
	s_nop 1
	v_permlane32_swap_b32_e32 v94, v95
	s_and_saveexec_b64 s[30:31], s[4:5]
	s_cbranch_execz .LBB0_1083
	s_waitcnt lgkmcnt(0)
	v_add_f32_e32 v94, v94, v95
	ds_write_b32 v228, v94 offset:2304
.LBB0_1083:
	s_or_b64 exec, exec, s[30:31]
	v_mul_f32_e32 v94, v35, v35
	s_waitcnt lgkmcnt(0)
	v_mul_f32_e32 v95, v37, v37
	v_fmac_f32_e32 v94, v34, v34
	v_fmac_f32_e32 v95, v36, v36
	v_add_f32_e32 v94, v94, v95
	v_mul_f32_e32 v95, v31, v31
	v_mul_f32_e32 v96, v33, v33
	v_fmac_f32_e32 v95, v30, v30
	v_fmac_f32_e32 v96, v32, v32
	v_add_f32_e32 v95, v95, v96
	v_add_f32_e32 v94, v95, v94
	v_mul_f32_e32 v95, v27, v27
	v_mul_f32_e32 v96, v29, v29
	v_fmac_f32_e32 v95, v26, v26
	v_fmac_f32_e32 v96, v28, v28
	v_add_f32_e32 v95, v95, v96
	v_add_f32_e32 v94, v95, v94
	v_mul_f32_e32 v95, v23, v23
	v_mul_f32_e32 v96, v25, v25
	v_fmac_f32_e32 v95, v22, v22
	v_fmac_f32_e32 v96, v24, v24
	v_add_f32_e32 v95, v95, v96
	v_add_f32_e32 v94, v95, v94
	v_mov_b32_e32 v95, v94
	s_nop 1
	v_permlane16_swap_b32_e32 v94, v95
	s_waitcnt lgkmcnt(0)
	v_add_f32_e32 v94, v94, v95
	v_mov_b32_e32 v95, v94
	s_nop 1
	v_permlane32_swap_b32_e32 v94, v95
	s_and_saveexec_b64 s[30:31], s[4:5]
	s_cbranch_execz .LBB0_1085
	s_waitcnt lgkmcnt(0)
	v_add_f32_e32 v94, v94, v95
	ds_write_b32 v228, v94 offset:2560
.LBB0_1085:
	s_or_b64 exec, exec, s[30:31]
	v_mul_f32_e32 v94, v19, v19
	s_waitcnt lgkmcnt(0)
	v_mul_f32_e32 v95, v21, v21
	v_fmac_f32_e32 v94, v18, v18
	v_fmac_f32_e32 v95, v20, v20
	v_add_f32_e32 v94, v94, v95
	v_mul_f32_e32 v95, v15, v15
	v_mul_f32_e32 v96, v17, v17
	v_fmac_f32_e32 v95, v14, v14
	v_fmac_f32_e32 v96, v16, v16
	v_add_f32_e32 v95, v95, v96
	v_add_f32_e32 v94, v95, v94
	v_mul_f32_e32 v95, v11, v11
	v_mul_f32_e32 v96, v13, v13
	v_fmac_f32_e32 v95, v10, v10
	v_fmac_f32_e32 v96, v12, v12
	v_add_f32_e32 v95, v95, v96
	v_add_f32_e32 v94, v95, v94
	v_mul_f32_e32 v95, v7, v7
	v_mul_f32_e32 v96, v9, v9
	v_fmac_f32_e32 v95, v6, v6
	v_fmac_f32_e32 v96, v8, v8
	v_add_f32_e32 v95, v95, v96
	v_add_f32_e32 v94, v95, v94
	v_mov_b32_e32 v95, v94
	s_nop 1
	v_permlane16_swap_b32_e32 v94, v95
	s_waitcnt lgkmcnt(0)
	v_add_f32_e32 v94, v94, v95
	v_mov_b32_e32 v95, v94
	s_nop 1
	v_permlane32_swap_b32_e32 v94, v95
	s_and_saveexec_b64 s[30:31], s[4:5]
	s_cbranch_execz .LBB0_1087
	s_waitcnt lgkmcnt(0)
	v_add_f32_e32 v94, v94, v95
	ds_write_b32 v228, v94 offset:2816

.LBB0_1106:
	v_mul_f32_e32 v147, v147, v147
	v_mul_f32_e32 v143, v143, v143
	v_mul_f32_e32 v139, v139, v139
	v_mul_f32_e32 v135, v135, v135
	v_fmac_f32_e32 v147, v146, v146
	v_mul_f32_e32 v146, v149, v149
	v_fmac_f32_e32 v143, v142, v142
	v_mul_f32_e32 v142, v145, v145
	v_fmac_f32_e32 v139, v138, v138
	v_mul_f32_e32 v138, v141, v141
	v_fmac_f32_e32 v135, v134, v134
	v_mul_f32_e32 v134, v137, v137
	v_fmac_f32_e32 v146, v148, v148
	v_fmac_f32_e32 v142, v144, v144
	v_fmac_f32_e32 v138, v140, v140
	v_fmac_f32_e32 v134, v136, v136
	v_add_f32_e32 v146, v147, v146
	v_add_f32_e32 v142, v143, v142
	v_add_f32_e32 v138, v139, v138
	v_add_f32_e32 v134, v135, v134
	v_add_f32_e32 v142, v146, v142
	v_add_f32_e32 v134, v138, v134
	v_add_f32_e32 v134, v142, v134
	v_mov_b32_e32 v135, v134
	s_nop 1
	v_permlane16_swap_b32_e32 v134, v135
	s_waitcnt lgkmcnt(0)
	v_add_f32_e32 v134, v134, v135
	v_mov_b32_e32 v135, v134
	s_nop 1
	v_permlane32_swap_b32_e32 v134, v135
	s_and_saveexec_b64 s[30:31], s[4:5]
	s_cbranch_execz .LBB0_1108
	s_waitcnt lgkmcnt(0)
	v_add_f32_e32 v134, v134, v135
	ds_write_b32 v228, v134

.LBB0_1114:
	v_mul_f32_e32 v131, v131, v131
	v_mul_f32_e32 v127, v127, v127
	v_mul_f32_e32 v123, v123, v123
	v_mul_f32_e32 v119, v119, v119
	v_fmac_f32_e32 v131, v130, v130
	v_mul_f32_e32 v130, v133, v133
	v_fmac_f32_e32 v127, v126, v126
	v_mul_f32_e32 v126, v129, v129
	v_fmac_f32_e32 v123, v122, v122
	v_mul_f32_e32 v122, v125, v125
	v_fmac_f32_e32 v119, v118, v118
	v_mul_f32_e32 v118, v121, v121
	v_fmac_f32_e32 v130, v132, v132
	v_fmac_f32_e32 v126, v128, v128
	v_fmac_f32_e32 v122, v124, v124
	v_fmac_f32_e32 v118, v120, v120
	v_add_f32_e32 v130, v131, v130
	v_add_f32_e32 v126, v127, v126
	v_add_f32_e32 v122, v123, v122
	v_add_f32_e32 v118, v119, v118
	v_add_f32_e32 v126, v130, v126
	v_add_f32_e32 v118, v122, v118
	v_add_f32_e32 v118, v126, v118
	v_mov_b32_e32 v119, v118
	s_nop 1
	v_permlane16_swap_b32_e32 v118, v119
	s_waitcnt lgkmcnt(0)
	v_add_f32_e32 v118, v118, v119
	v_mov_b32_e32 v119, v118
	s_nop 1
	v_permlane32_swap_b32_e32 v118, v119
	s_and_saveexec_b64 s[30:31], s[4:5]
	s_cbranch_execz .LBB0_1116
	s_waitcnt lgkmcnt(0)
	v_add_f32_e32 v118, v118, v119
	ds_write_b32 v229, v118

.LBB0_1122:
	v_mul_f32_e32 v107, v107, v107
	v_mul_f32_e32 v99, v99, v99
	v_mul_f32_e32 v91, v91, v91
	v_mul_f32_e32 v87, v87, v87
	v_fmac_f32_e32 v107, v106, v106
	v_mul_f32_e32 v106, v109, v109
	v_fmac_f32_e32 v99, v98, v98
	v_mul_f32_e32 v98, v101, v101
	v_fmac_f32_e32 v91, v90, v90
	v_mul_f32_e32 v90, v93, v93
	v_fmac_f32_e32 v87, v86, v86
	v_mul_f32_e32 v86, v89, v89
	v_fmac_f32_e32 v106, v108, v108
	v_fmac_f32_e32 v98, v100, v100
	v_fmac_f32_e32 v90, v92, v92
	v_fmac_f32_e32 v86, v88, v88
	v_add_f32_e32 v106, v107, v106
	v_add_f32_e32 v98, v99, v98
	v_add_f32_e32 v90, v91, v90
	v_add_f32_e32 v86, v87, v86
	v_add_f32_e32 v98, v106, v98
	v_add_f32_e32 v86, v90, v86
	v_add_f32_e32 v86, v98, v86
	v_mov_b32_e32 v87, v86
	s_nop 1
	v_permlane16_swap_b32_e32 v86, v87
	s_waitcnt lgkmcnt(0)
	v_add_f32_e32 v86, v86, v87
	v_mov_b32_e32 v87, v86
	s_nop 1
	v_permlane32_swap_b32_e32 v86, v87
	s_and_saveexec_b64 s[30:31], s[4:5]
	s_cbranch_execz .LBB0_1124
	s_waitcnt lgkmcnt(0)
	v_add_f32_e32 v86, v86, v87
	ds_write_b32 v230, v86

.LBB0_1130:
	v_mul_f32_e32 v83, v83, v83
	v_mul_f32_e32 v79, v79, v79
	v_mul_f32_e32 v75, v75, v75
	v_mul_f32_e32 v71, v71, v71
	v_fmac_f32_e32 v83, v82, v82
	v_mul_f32_e32 v82, v85, v85
	v_fmac_f32_e32 v79, v78, v78
	v_mul_f32_e32 v78, v81, v81
	v_fmac_f32_e32 v75, v74, v74
	v_mul_f32_e32 v74, v77, v77
	v_fmac_f32_e32 v71, v70, v70
	v_mul_f32_e32 v70, v73, v73
	v_fmac_f32_e32 v82, v84, v84
	v_fmac_f32_e32 v78, v80, v80
	v_fmac_f32_e32 v74, v76, v76
	v_fmac_f32_e32 v70, v72, v72
	v_add_f32_e32 v82, v83, v82
	v_add_f32_e32 v78, v79, v78
	v_add_f32_e32 v74, v75, v74
	v_add_f32_e32 v70, v71, v70
	v_add_f32_e32 v78, v82, v78
	v_add_f32_e32 v70, v74, v70
	v_add_f32_e32 v70, v78, v70
	v_mov_b32_e32 v71, v70
	s_nop 1
	v_permlane16_swap_b32_e32 v70, v71
	s_waitcnt lgkmcnt(0)
	v_add_f32_e32 v70, v70, v71
	v_mov_b32_e32 v71, v70
	s_nop 1
	v_permlane32_swap_b32_e32 v70, v71
	s_and_saveexec_b64 s[30:31], s[4:5]
	s_cbranch_execz .LBB0_1132
	s_waitcnt lgkmcnt(0)
	v_add_f32_e32 v70, v70, v71
	ds_write_b32 v231, v70

.LBB0_1138:
	v_mul_f32_e32 v67, v67, v67
	v_mul_f32_e32 v63, v63, v63
	v_mul_f32_e32 v59, v59, v59
	v_mul_f32_e32 v55, v55, v55
	v_fmac_f32_e32 v67, v66, v66
	v_mul_f32_e32 v66, v69, v69
	v_fmac_f32_e32 v63, v62, v62
	v_mul_f32_e32 v62, v65, v65
	v_fmac_f32_e32 v59, v58, v58
	v_mul_f32_e32 v58, v61, v61
	v_fmac_f32_e32 v55, v54, v54
	v_mul_f32_e32 v54, v57, v57
	v_fmac_f32_e32 v66, v68, v68
	v_fmac_f32_e32 v62, v64, v64
	v_fmac_f32_e32 v58, v60, v60
	v_fmac_f32_e32 v54, v56, v56
	v_add_f32_e32 v66, v67, v66
	v_add_f32_e32 v62, v63, v62
	v_add_f32_e32 v58, v59, v58
	v_add_f32_e32 v54, v55, v54
	v_add_f32_e32 v62, v66, v62
	v_add_f32_e32 v54, v58, v54
	v_add_f32_e32 v54, v54, v62
	v_mov_b32_e32 v55, v54
	s_nop 1
	v_permlane16_swap_b32_e32 v54, v55
	s_waitcnt lgkmcnt(0)
	v_add_f32_e32 v54, v54, v55
	v_mov_b32_e32 v55, v54
	s_nop 1
	v_permlane32_swap_b32_e32 v54, v55
	s_and_saveexec_b64 s[30:31], s[4:5]
	s_cbranch_execz .LBB0_1140
	s_waitcnt lgkmcnt(0)
	v_add_f32_e32 v54, v54, v55
	ds_write_b32 v232, v54

.LBB0_1146:
	v_mul_f32_e32 v51, v51, v51
	v_mul_f32_e32 v47, v47, v47
	v_mul_f32_e32 v43, v43, v43
	v_mul_f32_e32 v39, v39, v39
	v_fmac_f32_e32 v51, v50, v50
	v_mul_f32_e32 v50, v53, v53
	v_fmac_f32_e32 v47, v46, v46
	v_mul_f32_e32 v46, v49, v49
	v_fmac_f32_e32 v43, v42, v42
	v_mul_f32_e32 v42, v45, v45
	v_fmac_f32_e32 v39, v38, v38
	v_mul_f32_e32 v38, v41, v41
	v_fmac_f32_e32 v50, v52, v52
	v_fmac_f32_e32 v46, v48, v48
	v_fmac_f32_e32 v42, v44, v44
	v_fmac_f32_e32 v38, v40, v40
	v_add_f32_e32 v50, v51, v50
	v_add_f32_e32 v46, v47, v46
	v_add_f32_e32 v42, v43, v42
	v_add_f32_e32 v38, v39, v38
	v_add_f32_e32 v46, v50, v46
	v_add_f32_e32 v38, v42, v38
	v_add_f32_e32 v38, v46, v38
	v_mov_b32_e32 v39, v38
	s_nop 1
	v_permlane16_swap_b32_e32 v38, v39
	s_waitcnt lgkmcnt(0)
	v_add_f32_e32 v38, v38, v39
	v_mov_b32_e32 v39, v38
	s_nop 1
	v_permlane32_swap_b32_e32 v38, v39
	s_and_saveexec_b64 s[30:31], s[4:5]
	s_cbranch_execz .LBB0_1148
	s_waitcnt lgkmcnt(0)
	v_add_f32_e32 v38, v38, v39
	ds_write_b32 v233, v38

.LBB0_1154:
	v_mul_f32_e32 v35, v35, v35
	v_mul_f32_e32 v31, v31, v31
	v_mul_f32_e32 v27, v27, v27
	v_mul_f32_e32 v23, v23, v23
	v_fmac_f32_e32 v35, v34, v34
	v_mul_f32_e32 v34, v37, v37
	v_fmac_f32_e32 v31, v30, v30
	v_mul_f32_e32 v30, v33, v33
	v_fmac_f32_e32 v27, v26, v26
	v_mul_f32_e32 v26, v29, v29
	v_fmac_f32_e32 v23, v22, v22
	v_mul_f32_e32 v22, v25, v25
	v_fmac_f32_e32 v34, v36, v36
	v_fmac_f32_e32 v30, v32, v32
	v_fmac_f32_e32 v26, v28, v28
	v_fmac_f32_e32 v22, v24, v24
	v_add_f32_e32 v34, v35, v34
	v_add_f32_e32 v30, v31, v30
	v_add_f32_e32 v26, v27, v26
	v_add_f32_e32 v22, v23, v22
	v_add_f32_e32 v30, v34, v30
	v_add_f32_e32 v22, v26, v22
	v_add_f32_e32 v22, v30, v22
	v_mov_b32_e32 v23, v22
	s_nop 1
	v_permlane16_swap_b32_e32 v22, v23
	s_waitcnt lgkmcnt(0)
	v_add_f32_e32 v22, v22, v23
	v_mov_b32_e32 v23, v22
	s_nop 1
	v_permlane32_swap_b32_e32 v22, v23
	s_and_saveexec_b64 s[30:31], s[4:5]
	s_cbranch_execz .LBB0_1156
	s_waitcnt lgkmcnt(0)
	v_add_f32_e32 v22, v22, v23
	ds_write_b32 v234, v22

.LBB0_1162:
	v_mul_f32_e32 v19, v19, v19
	v_mul_f32_e32 v15, v15, v15
	v_mul_f32_e32 v11, v11, v11
	v_mul_f32_e32 v7, v7, v7
	v_fmac_f32_e32 v19, v18, v18
	v_mul_f32_e32 v18, v21, v21
	v_fmac_f32_e32 v15, v14, v14
	v_mul_f32_e32 v14, v17, v17
	v_fmac_f32_e32 v11, v10, v10
	v_mul_f32_e32 v10, v13, v13
	v_fmac_f32_e32 v7, v6, v6
	v_mul_f32_e32 v6, v9, v9
	v_fmac_f32_e32 v18, v20, v20
	v_fmac_f32_e32 v14, v16, v16
	v_fmac_f32_e32 v10, v12, v12
	v_fmac_f32_e32 v6, v8, v8
	v_add_f32_e32 v18, v19, v18
	v_add_f32_e32 v14, v15, v14
	v_add_f32_e32 v10, v11, v10
	v_add_f32_e32 v6, v7, v6
	v_add_f32_e32 v14, v18, v14
	v_add_f32_e32 v6, v10, v6
	v_add_f32_e32 v6, v14, v6
	v_mov_b32_e32 v7, v6
	s_nop 1
	v_permlane16_swap_b32_e32 v6, v7
	s_waitcnt lgkmcnt(0)
	v_add_f32_e32 v6, v6, v7
	v_mov_b32_e32 v7, v6
	s_nop 1
	v_permlane32_swap_b32_e32 v6, v7
	s_and_saveexec_b64 s[10:11], s[4:5]
	s_cbranch_execz .LBB0_1164
	s_waitcnt lgkmcnt(0)
	v_add_f32_e32 v6, v6, v7
	ds_write_b32 v235, v6
